# attention body: fmac+mov fused into one v_fma for the running softmax sum (one less VALU per tile)
# speedup vs baseline: 1.0117x; 1.0087x over previous
; DI f32x4 mfma16(bf16x8 a, bf16x8 b, f32x4 c) { return __builtin_amdgcn_mfma_f32_16x16x32_bf16(a, b, c, 0, 0, 0); }
; __device__ void attn_unit(const Params& p, bool smp, int b, int chunk, int h, char* lds) {
;     ...
;     if (active) {
;       const u16* sK = sbase + cur * STG;
;       const u16* sV = sK + 64 * LR;
;       f32x4 st[4];
; #pragma unroll
;       for (int n = 0; n < 4; ++n) {
;         f32x4 a = {0.f, 0.f, 0.f, 0.f};
; #pragma unroll
;         for (int ks = 0; ks < 2; ++ks) a = mfma16(*reinterpret_cast<const bf16x8*>(sK + (n * 16 + fr) * LR + ks * 32 + fq * 8), aq[ks], a);
;         st[n] = a;
;       }
;       float mx = -1e30f;
;       const int wlo = (int)(mthis[0] >> (fq * 4)), whi = (int)(mthis[1] >> (fq * 4));
; #pragma unroll
;       for (int n = 0; n < 4; ++n) {
; #pragma unroll
;         for (int j = 0; j < 4; ++j) {
;           const uint32_t sel = (uint32_t)__builtin_amdgcn_sbfe(n < 2 ? wlo : whi, (n & 1) * 16 + j, 1);
;           st[n][j] = __uint_as_float((__float_as_uint(st[n][j]) & sel) | (0xf149f2cau & ~sel));
;           mx = fmaxf(mx, st[n][j]);
;         }
;       }
;       mx = fmaxf(mx, __shfl_xor(mx, 16));
;       mx = fmaxf(mx, __shfl_xor(mx, 32));
;       const float mnew = fmaxf(mrun, mx);
;       const float alpha = __builtin_amdgcn_exp2f(mrun - mnew);
;       mrun = mnew;
;       float ps = 0.f;
; #pragma unroll
;       for (int n = 0; n < 4; ++n)
; #pragma unroll
;         for (int j = 0; j < 4; ++j) { st[n][j] = __builtin_amdgcn_exp2f(st[n][j] - mnew); ps += st[n][j]; }
;       lrun = lrun * alpha + ps;
; #pragma unroll
;       for (int n = 0; n < 4; ++n)
; #pragma unroll
;         for (int j = 0; j < 4; ++j) Ot[n][j] *= alpha;
; #pragma unroll
;       for (int ks = 0; ks < 2; ++ks) {
;         const bf16x8 pb = pack8_bf16(st[2 * ks][0], st[2 * ks][1], st[2 * ks][2], st[2 * ks][3],
;                                      st[2 * ks + 1][0], st[2 * ks + 1][1], st[2 * ks + 1][2], st[2 * ks + 1][3]);
; #pragma unroll
;         for (int dt = 0; dt < 4; ++dt) {
;           const u16* vr = sV + (dt * 16 + fr) * LR + ks * 32 + fq * 4;
;           const u32x2 v0 = *reinterpret_cast<const u32x2*>(vr), v1 = *reinterpret_cast<const u32x2*>(vr + 16);
;           const u32x4 vv = {v0[0], v0[1], v1[0], v1[1]};
;           Ot[dt] = mfma16(__builtin_bit_cast(bf16x8, vv), pb, Ot[dt]);
;         }
;       }
.LBB0_286:
	s_mulk_i32 s0, 0x4800
	v_add3_u32 v86, v61, s0, v64
	v_add_u32_e32 v87, v86, v63
	ds_read_b128 v[66:69], v86
	ds_read_b128 v[88:91], v86 offset:64
	ds_read_b128 v[70:73], v86 offset:2304
	ds_read_b128 v[92:95], v86 offset:2368
	ds_read_b128 v[74:77], v86 offset:4608
	ds_read_b128 v[96:99], v86 offset:4672
	ds_read_b128 v[78:81], v86 offset:6912
	ds_read_b128 v[100:103], v86 offset:6976
	ds_read_b64 v[104:105], v87 offset:9216
	ds_read_b64 v[106:107], v87 offset:9248
	v_lshrrev_b32_e32 v0, v59, v56
	v_lshrrev_b32_e32 v57, v59, v57
	s_waitcnt lgkmcnt(8)
	v_mfma_f32_16x16x32_bf16 v[66:69], v[66:69], v[16:19], 0
	ds_read_b64 v[108:109], v87 offset:11520
	ds_read_b64 v[110:111], v87 offset:11552
	ds_read_b64 v[112:113], v87 offset:13824
	ds_read_b64 v[114:115], v87 offset:13856
	v_mfma_f32_16x16x32_bf16 v[66:69], v[88:91], v[20:23], v[66:69]
	s_waitcnt lgkmcnt(10)
	v_mfma_f32_16x16x32_bf16 v[70:73], v[70:73], v[16:19], 0
	ds_read_b64 v[116:117], v87 offset:16128
	ds_read_b64 v[118:119], v87 offset:16160
	ds_read_b64 v[122:123], v87 offset:9280
	ds_read_b64 v[124:125], v87 offset:9312
	v_mfma_f32_16x16x32_bf16 v[70:73], v[92:95], v[20:23], v[70:73]
	s_waitcnt lgkmcnt(12)
	v_mfma_f32_16x16x32_bf16 v[74:77], v[74:77], v[16:19], 0
	ds_read_b64 v[126:127], v87 offset:11584
	ds_read_b64 v[128:129], v87 offset:11616
	v_mfma_f32_16x16x32_bf16 v[74:77], v[96:99], v[20:23], v[74:77]
	s_waitcnt lgkmcnt(12)
	v_mfma_f32_16x16x32_bf16 v[78:81], v[78:81], v[16:19], 0
	ds_read_b64 v[130:131], v87 offset:13888
	ds_read_b64 v[132:133], v87 offset:13920
	v_mfma_f32_16x16x32_bf16 v[78:81], v[100:103], v[20:23], v[78:81]
	s_waitcnt lgkmcnt(12)
	ds_read_b64 v[82:83], v87 offset:16192
	ds_read_b64 v[84:85], v87 offset:16224
	v_bfe_i32 v134, v0, 0, 1
	v_bfe_i32 v135, v0, 1, 1
	v_bitop3_b32 v66, v66, s87, v134 bitop3:0xe4
	v_bitop3_b32 v67, v67, s87, v135 bitop3:0xe4
	v_bfe_i32 v134, v0, 2, 1
	v_bfe_i32 v135, v0, 3, 1
	v_bitop3_b32 v68, v68, s87, v134 bitop3:0xe4
	v_bitop3_b32 v69, v69, s87, v135 bitop3:0xe4
	v_max3_f32 v136, v66, v67, v68
	v_max_f32_e32 v136, v136, v69
	v_bfe_i32 v134, v0, 16, 1
	v_bfe_i32 v135, v0, 17, 1
	v_bitop3_b32 v70, v70, s87, v134 bitop3:0xe4
	v_bitop3_b32 v71, v71, s87, v135 bitop3:0xe4
	v_bfe_i32 v134, v0, 18, 1
	v_bfe_i32 v135, v0, 19, 1
	v_bitop3_b32 v72, v72, s87, v134 bitop3:0xe4
	v_bitop3_b32 v73, v73, s87, v135 bitop3:0xe4
	v_max3_f32 v136, v136, v70, v71
	v_max3_f32 v136, v136, v72, v73
	v_bfe_i32 v134, v57, 0, 1
	v_bfe_i32 v135, v57, 1, 1
	v_bitop3_b32 v74, v74, s87, v134 bitop3:0xe4
	v_bitop3_b32 v75, v75, s87, v135 bitop3:0xe4
	v_bfe_i32 v134, v57, 2, 1
	v_bfe_i32 v135, v57, 3, 1
	v_bitop3_b32 v76, v76, s87, v134 bitop3:0xe4
	v_bitop3_b32 v77, v77, s87, v135 bitop3:0xe4
	v_max3_f32 v136, v136, v74, v75
	v_max3_f32 v136, v136, v76, v77
	v_bfe_i32 v134, v57, 16, 1
	v_bfe_i32 v135, v57, 17, 1
	v_bitop3_b32 v78, v78, s87, v134 bitop3:0xe4
	v_bitop3_b32 v79, v79, s87, v135 bitop3:0xe4
	v_bfe_i32 v134, v57, 18, 1
	v_bfe_i32 v135, v57, 19, 1
	v_bitop3_b32 v80, v80, s87, v134 bitop3:0xe4
	v_bitop3_b32 v81, v81, s87, v135 bitop3:0xe4
	v_max3_f32 v136, v136, v78, v79
	v_max3_f32 v136, v136, v80, v81
	v_mov_b32_e32 v135, v136
	s_nop 1
	v_permlane32_swap_b32_e32 v135, v136
	v_max_f32_e32 v136, v135, v136
	v_mov_b32_e32 v135, v136
	s_nop 1
	v_permlane16_swap_b32_e32 v135, v136
	v_max3_f32 v134, v65, v135, v136
	v_sub_f32_e32 v56, v65, v134
	v_exp_f32_e32 v56, v56
	v_mov_b32_e32 v65, v134
	v_sub_f32_e32 v66, v66, v134
	v_exp_f32_e32 v66, v66
	v_sub_f32_e32 v67, v67, v134
	v_exp_f32_e32 v67, v67
	v_add_f32_e32 v135, 0, v66
	v_sub_f32_e32 v68, v68, v134
	v_exp_f32_e32 v68, v68
	v_add_f32_e32 v135, v67, v135
	v_sub_f32_e32 v69, v69, v134
	v_exp_f32_e32 v69, v69
	v_add_f32_e32 v135, v68, v135
	v_pk_mul_f32 v[34:35], v[34:35], v[56:57] op_sel_hi:[1,0]
	v_pk_mul_f32 v[32:33], v[32:33], v[56:57] op_sel_hi:[1,0]
	v_sub_f32_e32 v70, v70, v134
	v_exp_f32_e32 v70, v70
	v_add_f32_e32 v135, v69, v135
	v_sub_f32_e32 v71, v71, v134
	v_exp_f32_e32 v71, v71
	v_add_f32_e32 v135, v70, v135
	v_pk_mul_f32 v[14:15], v[14:15], v[56:57] op_sel_hi:[1,0]
	v_pk_mul_f32 v[12:13], v[12:13], v[56:57] op_sel_hi:[1,0]
	v_sub_f32_e32 v72, v72, v134
	v_exp_f32_e32 v72, v72
	v_add_f32_e32 v135, v71, v135
	v_sub_f32_e32 v73, v73, v134
	v_exp_f32_e32 v73, v73
	v_add_f32_e32 v135, v72, v135
	v_pk_mul_f32 v[6:7], v[6:7], v[56:57] op_sel_hi:[1,0]
	v_pk_mul_f32 v[4:5], v[4:5], v[56:57] op_sel_hi:[1,0]
	v_sub_f32_e32 v74, v74, v134
	v_exp_f32_e32 v74, v74
	v_add_f32_e32 v135, v73, v135
	v_sub_f32_e32 v75, v75, v134
	v_exp_f32_e32 v75, v75
	v_add_f32_e32 v135, v74, v135
	v_pk_mul_f32 v[10:11], v[10:11], v[56:57] op_sel_hi:[1,0]
	v_pk_mul_f32 v[8:9], v[8:9], v[56:57] op_sel_hi:[1,0]
	v_sub_f32_e32 v76, v76, v134
	v_exp_f32_e32 v76, v76
	v_add_f32_e32 v135, v75, v135
	v_sub_f32_e32 v77, v77, v134
	v_exp_f32_e32 v77, v77
	v_add_f32_e32 v135, v76, v135
	v_sub_f32_e32 v78, v78, v134
	v_exp_f32_e32 v78, v78
	v_add_f32_e32 v135, v77, v135
	v_sub_f32_e32 v79, v79, v134
	v_exp_f32_e32 v79, v79
	v_add_f32_e32 v135, v78, v135
	v_sub_f32_e32 v80, v80, v134
	v_exp_f32_e32 v80, v80
	v_add_f32_e32 v135, v79, v135
	v_sub_f32_e32 v81, v81, v134
	v_exp_f32_e32 v81, v81
	v_add_f32_e32 v135, v80, v135
	v_cvt_pk_bf16_f32 v88, v66, v67
	v_cvt_pk_bf16_f32 v89, v68, v69
	v_cvt_pk_bf16_f32 v90, v70, v71
	v_cvt_pk_bf16_f32 v91, v72, v73
	v_add_f32_e32 v135, v81, v135
	v_cvt_pk_bf16_f32 v92, v74, v75
	v_cvt_pk_bf16_f32 v93, v76, v77
	v_cvt_pk_bf16_f32 v94, v78, v79
	v_cvt_pk_bf16_f32 v95, v80, v81
	v_fma_f32 v62, v62, v56, v135
	s_waitcnt lgkmcnt(0)
	s_nop 0
	v_mfma_f32_16x16x32_bf16 v[32:35], v[104:107], v[88:91], v[32:35]
	v_mfma_f32_16x16x32_bf16 v[12:15], v[108:111], v[88:91], v[12:15]
	v_mfma_f32_16x16x32_bf16 v[4:7], v[112:115], v[88:91], v[4:7]
	v_mfma_f32_16x16x32_bf16 v[8:11], v[116:119], v[88:91], v[8:11]
	v_mfma_f32_16x16x32_bf16 v[32:35], v[122:125], v[92:95], v[32:35]
	v_mfma_f32_16x16x32_bf16 v[12:15], v[126:129], v[92:95], v[12:15]
	v_mfma_f32_16x16x32_bf16 v[4:7], v[130:133], v[92:95], v[4:7]
	v_mfma_f32_16x16x32_bf16 v[8:11], v[82:85], v[92:95], v[8:11]

; DI f32x4 mfma16(bf16x8 a, bf16x8 b, f32x4 c) { return __builtin_amdgcn_mfma_f32_16x16x32_bf16(a, b, c, 0, 0, 0); }
; __device__ void attn_unit(const Params& p, bool smp, int b, int chunk, int h, char* lds) {
;     ...
;     if (active) {
;       const u16* sK = sbase + cur * STG;
;       const u16* sV = sK + 64 * LR;
;       f32x4 st[4];
; #pragma unroll
;       for (int n = 0; n < 4; ++n) {
;         f32x4 a = {0.f, 0.f, 0.f, 0.f};
; #pragma unroll
;         for (int ks = 0; ks < 2; ++ks) a = mfma16(*reinterpret_cast<const bf16x8*>(sK + (n * 16 + fr) * LR + ks * 32 + fq * 8), aq[ks], a);
;         st[n] = a;
;       }
;       float mx = -1e30f;
;       const int wlo = (int)(mthis[0] >> (fq * 4)), whi = (int)(mthis[1] >> (fq * 4));
; #pragma unroll
;       for (int n = 0; n < 4; ++n) {
; #pragma unroll
;         for (int j = 0; j < 4; ++j) {
;           const uint32_t sel = (uint32_t)__builtin_amdgcn_sbfe(n < 2 ? wlo : whi, (n & 1) * 16 + j, 1);
;           st[n][j] = __uint_as_float((__float_as_uint(st[n][j]) & sel) | (0xf149f2cau & ~sel));
;           mx = fmaxf(mx, st[n][j]);
;         }
;       }
;       mx = fmaxf(mx, __shfl_xor(mx, 16));
;       mx = fmaxf(mx, __shfl_xor(mx, 32));
;       const float mnew = fmaxf(mrun, mx);
;       const float alpha = __builtin_amdgcn_exp2f(mrun - mnew);
;       mrun = mnew;
;       float ps = 0.f;
; #pragma unroll
;       for (int n = 0; n < 4; ++n)
; #pragma unroll
;         for (int j = 0; j < 4; ++j) { st[n][j] = __builtin_amdgcn_exp2f(st[n][j] - mnew); ps += st[n][j]; }
;       lrun = lrun * alpha + ps;
; #pragma unroll
;       for (int n = 0; n < 4; ++n)
; #pragma unroll
;         for (int j = 0; j < 4; ++j) Ot[n][j] *= alpha;
; #pragma unroll
;       for (int ks = 0; ks < 2; ++ks) {
;         const bf16x8 pb = pack8_bf16(st[2 * ks][0], st[2 * ks][1], st[2 * ks][2], st[2 * ks][3],
;                                      st[2 * ks + 1][0], st[2 * ks + 1][1], st[2 * ks + 1][2], st[2 * ks + 1][3]);
; #pragma unroll
;         for (int dt = 0; dt < 4; ++dt) {
;           const u16* vr = sV + (dt * 16 + fr) * LR + ks * 32 + fq * 4;
;           const u32x2 v0 = *reinterpret_cast<const u32x2*>(vr), v1 = *reinterpret_cast<const u32x2*>(vr + 16);
;           const u32x4 vv = {v0[0], v0[1], v1[0], v1[1]};
;           Ot[dt] = mfma16(__builtin_bit_cast(bf16x8, vv), pb, Ot[dt]);
;         }
;       }
.LBB0_298:
	s_mulk_i32 s50, 0x4800
	v_add3_u32 v86, v61, s50, v64
	v_add_u32_e32 v87, v86, v63
	ds_read_b128 v[66:69], v86
	ds_read_b128 v[88:91], v86 offset:64
	ds_read_b128 v[70:73], v86 offset:2304
	ds_read_b128 v[92:95], v86 offset:2368
	ds_read_b128 v[74:77], v86 offset:4608
	ds_read_b128 v[96:99], v86 offset:4672
	ds_read_b128 v[78:81], v86 offset:6912
	ds_read_b128 v[100:103], v86 offset:6976
	ds_read_b64 v[104:105], v87 offset:9216
	ds_read_b64 v[106:107], v87 offset:9248
	v_lshrrev_b32_e32 v0, v47, v56
	v_lshrrev_b32_e32 v57, v47, v57
	s_waitcnt lgkmcnt(8)
	v_mfma_f32_16x16x32_bf16 v[66:69], v[66:69], v[16:19], 0
	ds_read_b64 v[108:109], v87 offset:11520
	ds_read_b64 v[110:111], v87 offset:11552
	ds_read_b64 v[112:113], v87 offset:13824
	ds_read_b64 v[114:115], v87 offset:13856
	v_mfma_f32_16x16x32_bf16 v[66:69], v[88:91], v[20:23], v[66:69]
	s_waitcnt lgkmcnt(10)
	v_mfma_f32_16x16x32_bf16 v[70:73], v[70:73], v[16:19], 0
	ds_read_b64 v[116:117], v87 offset:16128
	ds_read_b64 v[118:119], v87 offset:16160
	ds_read_b64 v[122:123], v87 offset:9280
	ds_read_b64 v[124:125], v87 offset:9312
	v_mfma_f32_16x16x32_bf16 v[70:73], v[92:95], v[20:23], v[70:73]
	s_waitcnt lgkmcnt(12)
	v_mfma_f32_16x16x32_bf16 v[74:77], v[74:77], v[16:19], 0
	ds_read_b64 v[126:127], v87 offset:11584
	ds_read_b64 v[128:129], v87 offset:11616
	v_mfma_f32_16x16x32_bf16 v[74:77], v[96:99], v[20:23], v[74:77]
	s_waitcnt lgkmcnt(12)
	v_mfma_f32_16x16x32_bf16 v[78:81], v[78:81], v[16:19], 0
	ds_read_b64 v[130:131], v87 offset:13888
	ds_read_b64 v[132:133], v87 offset:13920
	v_mfma_f32_16x16x32_bf16 v[78:81], v[100:103], v[20:23], v[78:81]
	s_waitcnt lgkmcnt(12)
	ds_read_b64 v[82:83], v87 offset:16192
	ds_read_b64 v[84:85], v87 offset:16224
	v_bfe_i32 v134, v0, 0, 1
	v_bfe_i32 v135, v0, 1, 1
	v_bitop3_b32 v66, v66, s87, v134 bitop3:0xe4
	v_bitop3_b32 v67, v67, s87, v135 bitop3:0xe4
	v_bfe_i32 v134, v0, 2, 1
	v_bfe_i32 v135, v0, 3, 1
	v_bitop3_b32 v68, v68, s87, v134 bitop3:0xe4
	v_bitop3_b32 v69, v69, s87, v135 bitop3:0xe4
	v_max3_f32 v136, v66, v67, v68
	v_max_f32_e32 v136, v136, v69
	v_bfe_i32 v134, v0, 16, 1
	v_bfe_i32 v135, v0, 17, 1
	v_bitop3_b32 v70, v70, s87, v134 bitop3:0xe4
	v_bitop3_b32 v71, v71, s87, v135 bitop3:0xe4
	v_bfe_i32 v134, v0, 18, 1
	v_bfe_i32 v135, v0, 19, 1
	v_bitop3_b32 v72, v72, s87, v134 bitop3:0xe4
	v_bitop3_b32 v73, v73, s87, v135 bitop3:0xe4
	v_max3_f32 v136, v136, v70, v71
	v_max3_f32 v136, v136, v72, v73
	v_bfe_i32 v134, v57, 0, 1
	v_bfe_i32 v135, v57, 1, 1
	v_bitop3_b32 v74, v74, s87, v134 bitop3:0xe4
	v_bitop3_b32 v75, v75, s87, v135 bitop3:0xe4
	v_bfe_i32 v134, v57, 2, 1
	v_bfe_i32 v135, v57, 3, 1
	v_bitop3_b32 v76, v76, s87, v134 bitop3:0xe4
	v_bitop3_b32 v77, v77, s87, v135 bitop3:0xe4
	v_max3_f32 v136, v136, v74, v75
	v_max3_f32 v136, v136, v76, v77
	v_bfe_i32 v134, v57, 16, 1
	v_bfe_i32 v135, v57, 17, 1
	v_bitop3_b32 v78, v78, s87, v134 bitop3:0xe4
	v_bitop3_b32 v79, v79, s87, v135 bitop3:0xe4
	v_bfe_i32 v134, v57, 18, 1
	v_bfe_i32 v135, v57, 19, 1
	v_bitop3_b32 v80, v80, s87, v134 bitop3:0xe4
	v_bitop3_b32 v81, v81, s87, v135 bitop3:0xe4
	v_max3_f32 v136, v136, v78, v79
	v_max3_f32 v136, v136, v80, v81
	v_mov_b32_e32 v135, v136
	s_nop 1
	v_permlane32_swap_b32_e32 v135, v136
	v_max_f32_e32 v136, v135, v136
	v_mov_b32_e32 v135, v136
	s_nop 1
	v_permlane16_swap_b32_e32 v135, v136
	v_max3_f32 v134, v65, v135, v136
	v_sub_f32_e32 v56, v65, v134
	v_exp_f32_e32 v56, v56
	v_mov_b32_e32 v65, v134
	v_sub_f32_e32 v66, v66, v134
	v_exp_f32_e32 v66, v66
	v_sub_f32_e32 v67, v67, v134
	v_exp_f32_e32 v67, v67
	v_add_f32_e32 v135, 0, v66
	v_sub_f32_e32 v68, v68, v134
	v_exp_f32_e32 v68, v68
	v_add_f32_e32 v135, v67, v135
	v_sub_f32_e32 v69, v69, v134
	v_exp_f32_e32 v69, v69
	v_add_f32_e32 v135, v68, v135
	v_pk_mul_f32 v[42:43], v[42:43], v[56:57] op_sel_hi:[1,0]
	v_pk_mul_f32 v[40:41], v[40:41], v[56:57] op_sel_hi:[1,0]
	v_sub_f32_e32 v70, v70, v134
	v_exp_f32_e32 v70, v70
	v_add_f32_e32 v135, v69, v135
	v_sub_f32_e32 v71, v71, v134
	v_exp_f32_e32 v71, v71
	v_add_f32_e32 v135, v70, v135
	v_pk_mul_f32 v[14:15], v[14:15], v[56:57] op_sel_hi:[1,0]
	v_pk_mul_f32 v[12:13], v[12:13], v[56:57] op_sel_hi:[1,0]
	v_sub_f32_e32 v72, v72, v134
	v_exp_f32_e32 v72, v72
	v_add_f32_e32 v135, v71, v135
	v_sub_f32_e32 v73, v73, v134
	v_exp_f32_e32 v73, v73
	v_add_f32_e32 v135, v72, v135
	v_pk_mul_f32 v[6:7], v[6:7], v[56:57] op_sel_hi:[1,0]
	v_pk_mul_f32 v[4:5], v[4:5], v[56:57] op_sel_hi:[1,0]
	v_sub_f32_e32 v74, v74, v134
	v_exp_f32_e32 v74, v74
	v_add_f32_e32 v135, v73, v135
	v_sub_f32_e32 v75, v75, v134
	v_exp_f32_e32 v75, v75
	v_add_f32_e32 v135, v74, v135
	v_pk_mul_f32 v[10:11], v[10:11], v[56:57] op_sel_hi:[1,0]
	v_pk_mul_f32 v[8:9], v[8:9], v[56:57] op_sel_hi:[1,0]
	v_sub_f32_e32 v76, v76, v134
	v_exp_f32_e32 v76, v76
	v_add_f32_e32 v135, v75, v135
	v_sub_f32_e32 v77, v77, v134
	v_exp_f32_e32 v77, v77
	v_add_f32_e32 v135, v76, v135
	v_sub_f32_e32 v78, v78, v134
	v_exp_f32_e32 v78, v78
	v_add_f32_e32 v135, v77, v135
	v_sub_f32_e32 v79, v79, v134
	v_exp_f32_e32 v79, v79
	v_add_f32_e32 v135, v78, v135
	v_sub_f32_e32 v80, v80, v134
	v_exp_f32_e32 v80, v80
	v_add_f32_e32 v135, v79, v135
	v_sub_f32_e32 v81, v81, v134
	v_exp_f32_e32 v81, v81
	v_add_f32_e32 v135, v80, v135
	v_cvt_pk_bf16_f32 v88, v66, v67
	v_cvt_pk_bf16_f32 v89, v68, v69
	v_cvt_pk_bf16_f32 v90, v70, v71
	v_cvt_pk_bf16_f32 v91, v72, v73
	v_add_f32_e32 v135, v81, v135
	v_cvt_pk_bf16_f32 v92, v74, v75
	v_cvt_pk_bf16_f32 v93, v76, v77
	v_cvt_pk_bf16_f32 v94, v78, v79
	v_cvt_pk_bf16_f32 v95, v80, v81
	v_fma_f32 v62, v62, v56, v135
	s_waitcnt lgkmcnt(0)
	s_nop 0
	v_mfma_f32_16x16x32_bf16 v[40:43], v[104:107], v[88:91], v[40:43]
	v_mfma_f32_16x16x32_bf16 v[12:15], v[108:111], v[88:91], v[12:15]
	v_mfma_f32_16x16x32_bf16 v[4:7], v[112:115], v[88:91], v[4:7]
	v_mfma_f32_16x16x32_bf16 v[8:11], v[116:119], v[88:91], v[8:11]
	v_mfma_f32_16x16x32_bf16 v[40:43], v[122:125], v[92:95], v[40:43]
	v_mfma_f32_16x16x32_bf16 v[12:15], v[126:129], v[92:95], v[12:15]
	v_mfma_f32_16x16x32_bf16 v[4:7], v[130:133], v[92:95], v[4:7]
	v_mfma_f32_16x16x32_bf16 v[8:11], v[82:85], v[92:95], v[8:11]
